# P7 entry: prompt retention-state counter peeked with each work-queue fetch, poll round trip skipped when already complete
# speedup vs baseline: 1.0099x; 1.0099x over previous
.LBB0_661:
	s_and_saveexec_b64 s[4:5], s[6:7]
	s_cbranch_execz .LBB0_665
	s_mov_b64 s[10:11], exec
	v_mbcnt_lo_u32_b32 v0, s10, 0
	v_mbcnt_hi_u32_b32 v0, s11, v0
	v_cmp_eq_u32_e32 vcc, 0, v0
	s_and_saveexec_b64 s[8:9], vcc
	s_cbranch_execz .LBB0_664
	s_bcnt1_i32_b64 s0, s[10:11]
	v_mov_b32_e32 v2, s0
	v_mov_b32_e32 v254, 0x30028
	global_load_dword v254, v254, s[14:15] sc1
	global_atomic_add v2, v1, v2, s[14:15] sc0

.LBB0_757:
	s_waitcnt vmcnt(0)
	s_waitcnt vmcnt(63) expcnt(7) lgkmcnt(15)
	s_barrier
	s_mov_b64 s[4:5], exec
	v_readlane_b32 s0, v255, 6
	v_readlane_b32 s1, v255, 7
	s_and_b64 s[0:1], s[4:5], s[0:1]
	s_mov_b64 exec, s[0:1]
	s_cbranch_execz .LBB0_809
	v_readlane_b32 s6, v255, 3
	v_readlane_b32 s7, v255, 4
	v_mov_b32_e32 v0, 0
	s_mov_b32 s8, 0
	s_nop 4
	v_readfirstlane_b32 s9, v254
	s_cmp_ge_u32 s9, 32
	s_cbranch_scc1 .Lp7_acq
